# grid barrier: extra un-waited L2 write-back by local arriver number 3*nloc/4 (instead of nloc/2)
# speedup vs baseline: 1.0056x; 1.0056x over previous
.LBB0_41:
	s_or_b64 exec, exec, s[6:7]
	v_cvt_f32_u32_e32 v6, v4
	s_waitcnt vmcnt(0)
	v_readfirstlane_b32 s6, v5
	v_sub_u32_e32 v5, 0, v4
	v_rcp_iflag_f32_e32 v6, v6
	v_add_u32_e32 v7, s6, v2
	v_mul_f32_e32 v6, 0x4f7ffffe, v6
	v_cvt_u32_f32_e32 v6, v6
	v_mul_lo_u32 v2, v5, v6
	v_mul_hi_u32 v2, v6, v2
	v_add_u32_e32 v2, v6, v2
	v_mul_hi_u32 v2, v7, v2
	v_mul_lo_u32 v5, v2, v4
	v_sub_u32_e32 v5, v7, v5
	v_add_u32_e32 v6, 1, v2
	v_sub_u32_e32 v8, v5, v4
	v_cmp_ge_u32_e32 vcc, v5, v4
	s_nop 1
	v_cndmask_b32_e32 v2, v2, v6, vcc
	v_cndmask_b32_e32 v5, v5, v8, vcc
	v_add_u32_e32 v6, 1, v2
	v_cmp_ge_u32_e32 vcc, v5, v4
	v_add_u32_e32 v5, 1, v7
	s_nop 0
	v_cndmask_b32_e32 v2, v2, v6, vcc
	v_mul_lo_u32 v6, v4, v2
	v_add_u32_e32 v4, v6, v4
	v_cmp_ne_u32_e32 vcc, v5, v4
	s_and_saveexec_b64 s[6:7], vcc
	s_xor_b64 s[6:7], exec, s[6:7]
	s_cbranch_execz .LBB0_55
	v_sub_u32_e32 v8, v4, v6
	v_sub_u32_e32 v6, v7, v6
	v_lshrrev_b32_e32 v9, 2, v8
	v_sub_u32_e32 v8, v8, v9
	v_cmp_eq_u32_e32 vcc, v6, v8
	s_cbranch_vccz .Lbar_nomidwb
	buffer_wbl2 sc1
